# 10 of 20 grid barriers become group-local (32 workgroups sharing blockIdx%8 = same GEMM row panels): one atomic + poll on a per-group word
# speedup vs baseline: 1.0433x; 1.0010x over previous
; #define LAS __attribute__((address_space(3)))
; __global__ void __launch_bounds__(NWAVES * 64, 2) trunk_fwd(Args args) {
;     extern __shared__ __attribute__((aligned(16))) unsigned char lds_raw[];
;     LAS unsigned char* lds = (LAS unsigned char*)lds_raw;
;     const int Gk = gridDim.x, bx = blockIdx.x;
;     const int vcu = (Gk % 8 == 0) ? (bx % 8) * (Gk / 8) + bx / 8 : bx;
;     unsigned char* ws = args.ws;
;     float* X = args.out;
;     bf16* XB = (bf16*)(ws + WS_XB);
;     float* SS = (float*)(ws + WS_SS);
;     const float* ROPE = (const float*)(ws + WS_ROPE);
;     bf16* ACT0 = (bf16*)(ws + WS_ACT);
;     bf16* ACT1 = ACT0 + (size_t)M * DM;
;     bf16* ACT2 = ACT1 + (size_t)M * DM;
;     bf16* ACT3 = ACT2 + (size_t)M * DM;
;     ...
;     volatile LAS unsigned* MISC = (volatile LAS unsigned*)(lds + 147200);
;     if (threadIdx.x < 32) MISC[threadIdx.x] = 0u;
;     __syncthreads();
;     XcdBarrier bar; bar.bar = (unsigned*)ws; bar.x = 0; bar.st = MISC + 8;
;     if (args.ph_hi - args.ph_lo > 1) bar = xcd_barrier_post((unsigned*)ws, MISC + 8);
_Z9trunk_fwd4Args:
	s_mov_b32 s101, 0
	s_mov_b32 s100, 0
	s_load_dword s4, s[0:1], 0x88
	s_load_dwordx2 s[66:67], s[0:1], 0x80
	s_mov_b32 s64, s2
	s_add_u32 s2, s0, 0x88
	s_addc_u32 s3, s1, 0
	s_mov_b32 s90, s64
	v_writelane_b32 v253, s2, 0
	s_nop 1
	v_writelane_b32 v253, s3, 1
	s_waitcnt lgkmcnt(0)
	s_and_b32 s2, s4, 7
	v_writelane_b32 v253, s4, 2
	s_cmp_lg_u32 s2, 0
	s_cbranch_scc0 .LBB0_636
	s_load_dwordx16 s[48:63], s[0:1], 0x40
	v_cmp_gt_u32_e32 vcc, 32, v0
	s_and_saveexec_b64 s[4:5], vcc

; __device__ __forceinline__ unsigned xb_ld(unsigned* p)              { return __hip_atomic_load(p, __ATOMIC_RELAXED, __HIP_MEMORY_SCOPE_AGENT); }
; __device__ __forceinline__ unsigned xb_add(unsigned* p, unsigned v) { return __hip_atomic_fetch_add(p, v, __ATOMIC_RELAXED, __HIP_MEMORY_SCOPE_AGENT); }
; #define XB_SPIN(cond, bar) do { unsigned _sp = 0; while (cond) { __builtin_amdgcn_s_sleep(1); \
;     if ((++_sp & 255u) == 0u) { if (xb_ld(&(bar)[XB_TMO])) break; if (_sp > XB_SPIN_CAP) { atomicAdd(&(bar)[XB_TMO], 1u); break; } } } } while (0)
; __device__ __forceinline__ void xcd_barrier(const XcdBarrier& b) {
;     asm volatile("s_waitcnt vmcnt(0)" ::: "memory");
;     __syncthreads();
;     if (threadIdx.x == 0) {
;         unsigned* bar = b.bar;
;         __builtin_amdgcn_s_waitcnt(0);
;         unsigned nloc = b.st[0], nx = b.st[1];
;         if (nloc == 0u) { xcd_barrier_complete(bar, b.x, nloc, nx); b.st[0] = nloc; b.st[1] = nx; }
;         const unsigned old = xb_add(&bar[XB_XSUB(b.x)], 1u);
;         const unsigned gen = old / nloc;
;         if (old + 1u == (gen + 1u) * nloc) {
;             __builtin_amdgcn_fence(__ATOMIC_RELEASE, "agent");
;             asm volatile("s_waitcnt vmcnt(0)" ::: "memory");
;             const unsigned og = xb_add(&bar[XB_TOP], 1u);
;             const unsigned tg = og / nx;
;             if (og + 1u == (tg + 1u) * nx) xb_add(&bar[XB_TOPGEN], 1u);
;             else XB_SPIN(xb_ld(&bar[XB_TOPGEN]) == tg, bar);
;             __builtin_amdgcn_fence(__ATOMIC_ACQUIRE, "agent");
;             xb_add(&bar[XB_XGEN(b.x)], 1u);
;             asm volatile("s_waitcnt vmcnt(0)" ::: "memory");
;         } else {
;             XB_SPIN(xb_ld(&bar[XB_XGEN(b.x)]) == gen, bar);
;             __builtin_amdgcn_fence(__ATOMIC_ACQUIRE, "agent");
;             asm volatile("s_waitcnt vmcnt(0)" ::: "memory");
;         }
;     }
;     __syncthreads();
; }
; __global__ void __launch_bounds__(NWAVES * 64, 2) trunk_fwd(Args args) {
;     ...
;         if (ph + 1 < args.ph_hi) xcd_barrier(bar);
.LBB0_585:
	s_waitcnt vmcnt(0)
	s_waitcnt vmcnt(0) lgkmcnt(0)
	s_barrier
	s_mov_b64 s[0:1], exec
	v_readlane_b32 s2, v255, 38
	v_readlane_b32 s3, v255, 39
	s_and_b64 s[2:3], s[0:1], s[2:3]
	s_mov_b64 exec, s[2:3]
	s_cbranch_execz .LBB0_633
	s_lshr_b32 s2, 0x19cd30, s66
	s_and_b32 s2, s2, 1
	s_cmp_eq_u32 s2, 0
	s_cbranch_scc1 .Lmy_glob
	v_readlane_b32 s3, v253, 2
	s_nop 0
	s_cmp_lg_u32 s3, 0x100
	s_cbranch_scc1 .Lmy_glob
	s_add_i32 s100, s100, 1
	s_and_b32 s2, s64, 7
	s_lshl_b32 s2, s2, 8
	s_add_u32 s2, s2, 0x3600
	s_add_u32 s2, s62, s2
	s_addc_u32 s3, s63, 0
	v_mov_b32_e32 v3, 1
	s_lshl_b32 s6, s100, 5
	s_mov_b32 s10, 0
	global_atomic_add v99, v3, s[2:3]
.Lmy_lspin:
	global_load_dword v5, v99, s[2:3] sc1
	s_waitcnt vmcnt(0)
	v_readfirstlane_b32 s7, v5
	s_cmp_ge_u32 s7, s6
	s_cbranch_scc1 .Lmy_ldone
	s_sleep 1
	s_add_i32 s10, s10, 1
	s_cmp_lt_u32 s10, 0x2000
	s_cbranch_scc1 .Lmy_lspin
.Lmy_ldone:
	buffer_inv sc1
	s_waitcnt vmcnt(0)
	s_branch .LBB0_633
.Lmy_glob:
	v_readlane_b32 s2, v255, 36
	s_waitcnt vmcnt(0) expcnt(0) lgkmcnt(0)
	s_nop 0
	v_mov_b32_e32 v2, s2
	ds_read_b32 v4, v2
	v_readlane_b32 s2, v255, 37
	s_waitcnt lgkmcnt(0)
	v_cmp_ne_u32_e32 vcc, 0, v4
	v_mov_b32_e32 v2, s2
	ds_read_b32 v2, v2
	s_cbranch_vccnz .LBB0_601
	v_readlane_b32 s6, v253, 0
	v_readlane_b32 s7, v253, 1
	s_load_dwordx2 s[2:3], s[6:7], 0x4
	v_readlane_b32 s6, v253, 2
	s_waitcnt lgkmcnt(0)
	s_mul_i32 s2, s2, s6
	s_mul_i32 s2, s2, s3
	s_mov_b32 s3, 1
	s_branch .LBB0_589
